# NSA unit: kc/vc LDS staging loops unrolled (4 loads in flight), qk-gain loads for the softmax reference hoisted
# speedup vs baseline: 1.0065x; 1.0027x over previous
; DI void unpack8(const u32x4 w, float (&f)[8]) { f[0] = bflo(w.x); f[1] = bfhi(w.x); f[2] = bflo(w.y); f[3] = bfhi(w.y); f[4] = bflo(w.z); f[5] = bfhi(w.z); f[6] = bflo(w.w); f[7] = bfhi(w.w); }
; DI void nsa_wg_unit(const Args& a, int l, int b, int g, int tb, unsigned char* lds, int tid_in, bool stage) {
;     ...
;     for (int i = tid; i < 2048; i += 512) { const int row = i >> 3, ch = i & 7; *(u32x4*)(lds + AL_KC + row * KC_PB + ch * 16) = *(const u32x4*)(KC + row * 64 + ch * 8); }
;     for (int i = tid; i < 2048; i += 512) { const int row = i >> 5, ch = i & 31; const u32x4 v = *(const u32x4*)(VCT + row * 256 + ch * 8); u32x2* d = (u32x2*)(lds + AL_VC + row * VC_PB + ch * 16); u32x2 lo, hi; lo.x = v.x; lo.y = v.y; hi.x = v.z; hi.y = v.w; d[0] = lo; d[1] = hi; }
;     }
;     bf16x8 qf[NRT][4]; float gt[NRT][3]; bf16_t* orow[NRT];
;     { const bf16_t* zr = zb + (size_t)tk[0] * ZP;
; #pragma unroll
;       for (int dc = 0; dc < 4; ++dc) qf[0][dc] = *(const bf16x8*)(zr + C_Q + (g * 4 + head) * 64 + dc * 16 + 8 * h);
;       { const float* qg = a.in[4] + (size_t)l * 4 * 64; float qv[4][8]; float qs = 0.f;
; #pragma unroll
;         for (int dc = 0; dc < 4; ++dc) { unpack8(__builtin_bit_cast(u32x4, qf[0][dc]), qv[dc]);
; #pragma unroll
;             for (int e = 0; e < 8; ++e) qs += qv[dc][e] * qv[dc][e]; }
;         qs += __shfl_xor(qs, 32); const float rs = rsqrtf(qs * (1.0f / 64.0f) + 1e-6f) * QSC;
; #pragma unroll
;         for (int dc = 0; dc < 4; ++dc) { const f32x4 g0 = *(const f32x4*)(qg + dc * 16 + 8 * h), g1 = *(const f32x4*)(qg + dc * 16 + 8 * h + 4);
.LBB0_114:
	v_ashrrev_i32_e32 v8, 3, v3
	v_lshlrev_b32_e32 v4, 6, v8
	v_ashrrev_i32_e32 v5, 31, v4
	v_lshl_add_u64 v[4:5], v[4:5], 1, v[0:1]
	s_movk_i32 s100, 0x2000
	s_mov_b32 s101, 0
	v_lshl_add_u64 v[200:201], v[4:5], 0, s[100:101]
	s_movk_i32 s100, 0x4000
	v_lshl_add_u64 v[202:203], v[4:5], 0, s[100:101]
	s_movk_i32 s100, 0x6000
	v_lshl_add_u64 v[204:205], v[4:5], 0, s[100:101]
	global_load_dwordx4 v[236:239], v[4:5], off
	global_load_dwordx4 v[240:243], v[200:201], off
	global_load_dwordx4 v[244:247], v[202:203], off
	global_load_dwordx4 v[248:251], v[204:205], off
	v_mad_u64_u32 v[8:9], s[12:13], v8, s22, v[2:3]
	s_waitcnt vmcnt(3)
	ds_write_b128 v8, v[236:239]
	s_waitcnt vmcnt(2)
	ds_write_b128 v8, v[240:243] offset:9216
	s_waitcnt vmcnt(1)
	ds_write_b128 v8, v[244:247] offset:18432
	s_waitcnt vmcnt(0)
	ds_write_b128 v8, v[248:251] offset:27648
	s_or_b64 exec, exec, s[8:9]
	v_readlane_b32 s8, v254, 30
	s_add_u32 s6, s8, s6
	v_readlane_b32 s8, v254, 31
	s_addc_u32 s7, s8, s7
	v_lshlrev_b32_e32 v160, 4, v70
	v_lshl_add_u64 v[0:1], s[6:7], 0, v[160:161]
	v_add_u32_e32 v2, 0, v160
	s_mov_b64 s[6:7], 0
	v_mov_b32_e32 v3, v71
.LBB0_116:
	v_ashrrev_i32_e32 v8, 5, v3
	v_lshlrev_b32_e32 v4, 8, v8
	v_ashrrev_i32_e32 v5, 31, v4
	v_lshl_add_u64 v[4:5], v[4:5], 1, v[0:1]
	s_movk_i32 s100, 0x2000
	s_mov_b32 s101, 0
	v_lshl_add_u64 v[200:201], v[4:5], 0, s[100:101]
	s_movk_i32 s100, 0x4000
	v_lshl_add_u64 v[202:203], v[4:5], 0, s[100:101]
	s_movk_i32 s100, 0x6000
	v_lshl_add_u64 v[204:205], v[4:5], 0, s[100:101]
	global_load_dwordx4 v[236:239], v[4:5], off
	global_load_dwordx4 v[240:243], v[200:201], off
	global_load_dwordx4 v[244:247], v[202:203], off
	global_load_dwordx4 v[248:251], v[204:205], off
	s_movk_i32 s8, 0x208
	v_mul_lo_u32 v8, v8, s8
	s_mov_b32 s8, 0x9000
	v_add3_u32 v8, v2, v8, s8
	v_add_u32_e32 v9, 0x2080, v8
	v_add_u32_e32 v206, 0x4100, v8
	v_add_u32_e32 v207, 0x6180, v8
	s_waitcnt vmcnt(3)
	ds_write2_b64 v8, v[236:237], v[238:239] offset1:1
	s_waitcnt vmcnt(2)
	ds_write2_b64 v9, v[240:241], v[242:243] offset1:1
	s_waitcnt vmcnt(1)
	ds_write2_b64 v206, v[244:245], v[246:247] offset1:1
	s_waitcnt vmcnt(0)
	ds_write2_b64 v207, v[248:249], v[250:251] offset1:1
.LBB0_117:
	s_or_b64 exec, exec, s[0:1]
	s_and_b32 s33, s11, 31
	s_ashr_i32 s0, s10, 6
	s_lshl_b32 s1, s33, 6
	s_lshl_b32 s18, s0, 3
	v_writelane_b32 v254, s1, 51
	s_mul_i32 s6, s30, 0x2230000
	s_add_i32 s93, s18, s1
	v_readlane_b32 s1, v254, 28
	v_writelane_b32 v254, s6, 52
	s_mul_hi_i32 s2, s30, 0x2230000
	s_add_u32 s36, s1, s6
	v_readlane_b32 s1, v254, 29
	v_and_b32_e32 v33, 3, v71
	v_lshrrev_b32_e32 v74, 2, v70
	s_addc_u32 s37, s1, s2
	s_lshl_b32 s34, s24, 8
	v_or_b32_e32 v136, s93, v74
	v_mov_b64_e32 v[0:1], s[36:37]
	v_lshl_or_b32 v62, v33, 6, s34
	v_bfe_u32 v75, v71, 5, 1
	v_mad_i64_i32 v[80:81], s[6:7], v136, s3, v[0:1]
	v_lshlrev_b32_e32 v160, 1, v62
	v_lshl_add_u64 v[0:1], v[80:81], 0, v[160:161]
	v_lshlrev_b32_e32 v60, 4, v75
	v_mov_b32_e32 v61, v161
	v_lshl_add_u64 v[0:1], v[0:1], 0, v[60:61]
	global_load_dwordx4 v[76:79], v[0:1], off offset:3072
	global_load_dwordx4 v[64:67], v[0:1], off offset:3104
	global_load_dwordx4 v[50:53], v[0:1], off offset:3136
	global_load_dwordx4 v[42:45], v[0:1], off offset:3168
	s_lshl_b32 s29, s24, 2
	v_and_b32_e32 v149, 64, v217
	v_xor_b32_e32 v0, 32, v217
	v_add_u32_e32 v61, 64, v149
	v_cmp_lt_i32_e32 vcc, v0, v61
	s_mov_b64 s[6:7], 0x1600
	v_and_b32_e32 v73, 63, v71
	v_cndmask_b32_e32 v0, v217, v0, vcc
	v_and_b32_e32 v4, 32, v71
	v_lshlrev_b32_e32 v148, 2, v0
	global_load_dwordx4 v[24:27], v4, s[90:91] offset:16
	global_load_dwordx4 v[28:31], v4, s[90:91]
	global_load_dwordx4 v[16:19], v4, s[90:91] offset:80
	global_load_dwordx4 v[20:23], v4, s[90:91] offset:64
	global_load_dwordx4 v[8:11], v4, s[90:91] offset:144
	global_load_dwordx4 v[12:15], v4, s[90:91] offset:128
	global_load_dwordx4 v[0:3], v4, s[90:91] offset:208
	s_nop 0
	global_load_dwordx4 v[4:7], v4, s[90:91] offset:192
	s_mulk_i32 s0, 0x1080
	s_add_i32 s8, s0, 0
	s_add_i32 s9, s8, 0x19e00
	v_writelane_b32 v254, s2, 53
	v_ashrrev_i32_e32 v137, 31, v136
	v_lshlrev_b32_e32 v72, 3, v75
	s_mov_b64 s[0:1], 0
	s_movk_i32 s23, 0x3cf
	s_waitcnt vmcnt(0)
	v_lshlrev_b32_e32 v68, 16, v76
	v_and_b32_e32 v69, 0xffff0000, v76
	s_waitcnt vmcnt(9)
	v_lshlrev_b32_e32 v46, 16, v52
	s_waitcnt vmcnt(8)
; DI float bf1(bf16_t v) { return __uint_as_float(((unsigned)v) << 16); }
; DI void unpack8(const u32x4 w, float (&f)[8]) { f[0] = bflo(w.x); f[1] = bfhi(w.x); f[2] = bflo(w.y); f[3] = bfhi(w.y); f[4] = bflo(w.z); f[5] = bfhi(w.z); f[6] = bflo(w.w); f[7] = bfhi(w.w); }
; DI u32x4 pack8(const float (&f)[8]) { u32x4 w; w.x = cvtpk(f[0], f[1]); w.y = cvtpk(f[2], f[3]); w.z = cvtpk(f[4], f[5]); w.w = cvtpk(f[6], f[7]); return w; }
; DI void nsa_wg_unit(const Args& a, int l, int b, int g, int tb, unsigned char* lds, int tid_in, bool stage) {
;     ...
;         for (int dc = 0; dc < 4; ++dc) { unpack8(__builtin_bit_cast(u32x4, qf[0][dc]), qv[dc]);
; #pragma unroll
;             for (int e = 0; e < 8; ++e) qs += qv[dc][e] * qv[dc][e]; }
;         qs += __shfl_xor(qs, 32); const float rs = rsqrtf(qs * (1.0f / 64.0f) + 1e-6f) * QSC;
; #pragma unroll
;         for (int dc = 0; dc < 4; ++dc) { const f32x4 g0 = *(const f32x4*)(qg + dc * 16 + 8 * h), g1 = *(const f32x4*)(qg + dc * 16 + 8 * h + 4);
; #pragma unroll
;             for (int e = 0; e < 4; ++e) { qv[dc][e] = qv[dc][e] * rs * g0[e]; qv[dc][4 + e] = qv[dc][4 + e] * rs * g1[e]; }
;             qf[0][dc] = __builtin_bit_cast(bf16x8, pack8(qv[dc])); } }
; #pragma unroll
;       for (int br = 0; br < 3; ++br) gt[0][br] = 1.0f / (1.0f + __expf(-bf1(zr[C_NG + (g * 4 + head) * 3 + br])));
;       orow[0] = OB + ((size_t)b * SEQ + tk[0]) * 512 + (g * 4 + head) * 64 + 4 * h; }
;     float cref[3];
;     { const float* qg = a.in[4] + (size_t)l * 4 * 64; float mx[4];
; #pragma unroll
;       for (int k4 = 0; k4 < 4; ++k4) { float v = fabsf(qg[k4 * 64 + lane]);
; #pragma unroll
;           for (int o = 1; o < 64; o <<= 1) v = fmaxf(v, __shfl_xor(v, o));
;           mx[k4] = v; }
; #pragma unroll
;       for (int br = 0; br < 3; ++br) { const float bnd = 64.0f * QSC * mx[0] * mx[1 + br]; cref[br] = bnd > 64.0f ? bnd : 0.f; } }
	v_lshlrev_b32_e32 v36, 16, v43
	v_and_b32_e32 v37, 0xffff0000, v43
	v_lshlrev_b32_e32 v40, 16, v42
	v_and_b32_e32 v41, 0xffff0000, v42
	v_lshlrev_b32_e32 v42, 16, v53
	v_and_b32_e32 v43, 0xffff0000, v53
	v_and_b32_e32 v47, 0xffff0000, v52
	v_lshlrev_b32_e32 v52, 16, v65
	v_and_b32_e32 v53, 0xffff0000, v65
	v_lshlrev_b32_e32 v56, 16, v64
	v_and_b32_e32 v57, 0xffff0000, v64
	v_lshlrev_b32_e32 v64, 16, v77
	v_and_b32_e32 v65, 0xffff0000, v77
	v_pk_mul_f32 v[76:77], v[68:69], v[68:69]
	v_pk_mul_f32 v[108:109], v[64:65], v[64:65]
	v_add_f32_e32 v32, v76, v77
	v_lshlrev_b32_e32 v34, 16, v45
	v_and_b32_e32 v35, 0xffff0000, v45
	v_lshlrev_b32_e32 v38, 16, v44
	v_and_b32_e32 v39, 0xffff0000, v44
	v_lshlrev_b32_e32 v44, 16, v51
	v_and_b32_e32 v45, 0xffff0000, v51
	v_lshlrev_b32_e32 v48, 16, v50
	v_and_b32_e32 v49, 0xffff0000, v50
	v_lshlrev_b32_e32 v50, 16, v67
	v_and_b32_e32 v51, 0xffff0000, v67
	v_lshlrev_b32_e32 v54, 16, v66
	v_and_b32_e32 v55, 0xffff0000, v66
	v_lshlrev_b32_e32 v66, 16, v78
	v_and_b32_e32 v67, 0xffff0000, v78
	v_add_f32_e32 v32, v108, v32
	v_lshlrev_b32_e32 v58, 16, v79
	v_and_b32_e32 v59, 0xffff0000, v79
	v_pk_mul_f32 v[78:79], v[66:67], v[66:67]
	v_add_f32_e32 v32, v109, v32
	v_add_f32_e32 v32, v78, v32
	v_pk_mul_f32 v[106:107], v[58:59], v[58:59]
	v_add_f32_e32 v32, v79, v32
	v_add_f32_e32 v32, v106, v32
	v_pk_mul_f32 v[104:105], v[56:57], v[56:57]
	v_add_f32_e32 v32, v107, v32
	v_add_f32_e32 v32, v104, v32
	v_pk_mul_f32 v[100:101], v[52:53], v[52:53]
	v_add_f32_e32 v32, v105, v32
	v_add_f32_e32 v32, v100, v32
	v_pk_mul_f32 v[102:103], v[54:55], v[54:55]
	v_add_f32_e32 v32, v101, v32
	v_add_f32_e32 v32, v102, v32
	v_pk_mul_f32 v[98:99], v[50:51], v[50:51]
	v_add_f32_e32 v32, v103, v32
	v_add_f32_e32 v32, v98, v32
	v_pk_mul_f32 v[96:97], v[48:49], v[48:49]
	v_add_f32_e32 v32, v99, v32
	v_add_f32_e32 v32, v96, v32
	v_pk_mul_f32 v[92:93], v[44:45], v[44:45]
	v_add_f32_e32 v32, v97, v32
	v_add_f32_e32 v32, v92, v32
	v_pk_mul_f32 v[94:95], v[46:47], v[46:47]
	v_add_f32_e32 v32, v93, v32
	v_add_f32_e32 v32, v94, v32
	v_pk_mul_f32 v[90:91], v[42:43], v[42:43]
	v_add_f32_e32 v32, v95, v32
	v_add_f32_e32 v32, v90, v32
	v_pk_mul_f32 v[88:89], v[40:41], v[40:41]
	v_add_f32_e32 v32, v91, v32
	v_add_f32_e32 v32, v88, v32
	v_pk_mul_f32 v[84:85], v[36:37], v[36:37]
	v_add_f32_e32 v32, v89, v32
	v_add_f32_e32 v32, v84, v32
	v_pk_mul_f32 v[86:87], v[38:39], v[38:39]
	v_add_f32_e32 v32, v85, v32
	v_add_f32_e32 v32, v86, v32
	v_pk_mul_f32 v[82:83], v[34:35], v[34:35]
	v_add_f32_e32 v32, v87, v32
	v_add_f32_e32 v32, v82, v32
	v_add_f32_e32 v76, v83, v32
	v_or_b32_e32 v32, s29, v33
	v_mul_u32_u24_e32 v32, 3, v32
	v_lshlrev_b32_e32 v160, 1, v32
	v_lshl_add_u64 v[78:79], v[80:81], 0, v[160:161]
	v_lshl_add_u64 v[80:81], v[78:79], 0, s[6:7]
	v_add_co_u32_e32 v78, vcc, s85, v78
	ds_bpermute_b32 v77, v148, v76
	s_nop 0
	v_addc_co_u32_e32 v79, vcc, 0, v79, vcc
	global_load_dword v32, v[78:79], off offset:1536
	global_load_ushort v139, v[80:81], off offset:4
	v_lshlrev_b32_e32 v80, 2, v73
	global_load_dword v63, v80, s[90:91]
	global_load_dword v81, v80, s[90:91] offset:768
	global_load_dword v206, v80, s[90:91] offset:256
	global_load_dword v207, v80, s[90:91] offset:512
	v_xor_b32_e32 v79, 1, v217
	v_cmp_lt_i32_e32 vcc, v79, v61
	s_waitcnt vmcnt(3)
	v_and_b32_e32 v78, 0x7fffffff, v63
	v_cndmask_b32_e32 v79, v217, v79, vcc
	v_lshlrev_b32_e32 v152, 2, v79
	ds_bpermute_b32 v78, v152, v78
	v_max_f32_e64 v63, |v63|, |v63|
	s_waitcnt vmcnt(2)
	v_and_b32_e32 v82, 0x7fffffff, v81
	ds_bpermute_b32 v82, v152, v82
	v_max_f32_e64 v81, |v81|, |v81|
	s_waitcnt lgkmcnt(1)
	v_max_f32_e32 v78, v78, v78
	v_max_f32_e32 v63, v63, v78
	v_xor_b32_e32 v78, 2, v217
	v_cmp_lt_i32_e32 vcc, v78, v61
	s_waitcnt lgkmcnt(0)
	v_max_f32_e32 v82, v82, v82
	v_max_f32_e32 v81, v81, v82
	v_cndmask_b32_e32 v78, v217, v78, vcc
	v_lshlrev_b32_e32 v153, 2, v78
	ds_bpermute_b32 v78, v153, v63
	ds_bpermute_b32 v82, v153, v81
	s_waitcnt lgkmcnt(1)
	v_max_f32_e32 v78, v78, v78
	v_max_f32_e32 v63, v63, v78
	v_xor_b32_e32 v78, 4, v217
	v_cmp_lt_i32_e32 vcc, v78, v61
	s_waitcnt lgkmcnt(0)
	v_max_f32_e32 v82, v82, v82
	v_max_f32_e32 v81, v81, v82
	v_cndmask_b32_e32 v78, v217, v78, vcc
	v_lshlrev_b32_e32 v154, 2, v78
	ds_bpermute_b32 v78, v154, v63
	ds_bpermute_b32 v82, v154, v81
	s_waitcnt lgkmcnt(1)
	v_max_f32_e32 v78, v78, v78
	v_max_f32_e32 v63, v63, v78
	v_xor_b32_e32 v78, 8, v217
	v_cmp_lt_i32_e32 vcc, v78, v61
	s_waitcnt lgkmcnt(0)
	v_max_f32_e32 v82, v82, v82
	v_max_f32_e32 v81, v81, v82
	v_cndmask_b32_e32 v78, v217, v78, vcc
	v_lshlrev_b32_e32 v150, 2, v78
	ds_bpermute_b32 v78, v150, v63
	ds_bpermute_b32 v82, v150, v81
	s_waitcnt lgkmcnt(1)
	v_max_f32_e32 v78, v78, v78
	v_max_f32_e32 v63, v63, v78
	v_xor_b32_e32 v78, 16, v217
	v_cmp_lt_i32_e32 vcc, v78, v61
	s_waitcnt lgkmcnt(0)
	v_max_f32_e32 v82, v82, v82
	v_max_f32_e32 v81, v81, v82
	v_cndmask_b32_e32 v61, v217, v78, vcc
	v_lshlrev_b32_e32 v151, 2, v61
	ds_bpermute_b32 v61, v151, v63
	ds_bpermute_b32 v82, v151, v81
	s_waitcnt lgkmcnt(1)
	v_max_f32_e32 v61, v61, v61
	v_max_f32_e32 v78, v63, v61
	s_waitcnt lgkmcnt(0)
	v_max_f32_e32 v82, v82, v82
	v_max_f32_e32 v96, v81, v82
	ds_bpermute_b32 v79, v148, v78
	ds_bpermute_b32 v97, v148, v96
	v_or_b32_e32 v81, 0xffffffc0, v73
	s_waitcnt vmcnt(1)
	v_mov_b32_e32 v61, v206
	v_and_b32_e32 v63, 0x7fffffff, v61
	ds_bpermute_b32 v63, v152, v63
	v_max_f32_e64 v61, |v61|, |v61|
	s_waitcnt lgkmcnt(0)
	v_max_f32_e32 v63, v63, v63
	v_max_f32_e32 v61, v61, v63
	ds_bpermute_b32 v63, v153, v61
	s_waitcnt lgkmcnt(0)
	v_max_f32_e32 v63, v63, v63
	v_max_f32_e32 v61, v61, v63
	ds_bpermute_b32 v63, v154, v61
	s_waitcnt lgkmcnt(0)
	v_max_f32_e32 v63, v63, v63
	v_max_f32_e32 v61, v61, v63
	ds_bpermute_b32 v63, v150, v61
	s_waitcnt lgkmcnt(0)
	v_max_f32_e32 v63, v63, v63
	v_max_f32_e32 v61, v61, v63
	ds_bpermute_b32 v63, v151, v61
	s_waitcnt lgkmcnt(0)
	v_max_f32_e32 v63, v63, v63
	v_max_f32_e32 v98, v61, v63
	ds_bpermute_b32 v99, v148, v98
	v_add_u32_e32 v80, s9, v80
	s_waitcnt vmcnt(0)
	v_mov_b32_e32 v61, v207
	v_and_b32_e32 v63, 0x7fffffff, v61
	ds_bpermute_b32 v63, v152, v63
	v_max_f32_e64 v61, |v61|, |v61|
	s_waitcnt lgkmcnt(0)
	v_max_f32_e32 v63, v63, v63
	v_max_f32_e32 v61, v61, v63
	ds_bpermute_b32 v63, v153, v61
	s_waitcnt lgkmcnt(0)
	v_max_f32_e32 v63, v63, v63
	v_max_f32_e32 v61, v61, v63
	ds_bpermute_b32 v63, v154, v61
	s_waitcnt lgkmcnt(0)
	v_max_f32_e32 v63, v63, v63
	v_max_f32_e32 v61, v61, v63
	ds_bpermute_b32 v63, v150, v61
	s_waitcnt lgkmcnt(0)
	v_max_f32_e32 v63, v63, v63
	v_max_f32_e32 v61, v61, v63
	ds_bpermute_b32 v63, v151, v61
	s_waitcnt lgkmcnt(0)
	v_max_f32_e32 v63, v63, v63
	v_max_f32_e32 v61, v61, v63
	ds_bpermute_b32 v63, v148, v61
